# v18 + SwiGLU epilogue algebra: rcp(fma(e,m,m)) with m=mean(x^2)+eps replaces rs^2*rcp(1+e); one multiply less per output element (63/64)
# speedup vs baseline: 1.0007x; 1.0006x over previous
; DI u32x4 pack8(const f32x4 v0, const f32x4 v1) { u32x4 w; w.x = cvt_pk_bf16(v0[0], v0[1]); w.y = cvt_pk_bf16(v0[2], v0[3]); w.z = cvt_pk_bf16(v1[0], v1[1]); w.w = cvt_pk_bf16(v1[2], v1[3]); return w; }
;     DI void operator()(const f32x4 (&acc)[2][2][4][2], const Unit& u, int wr, int wc, int fr, int fq) const {
;     ...
;         float ssv[8];
; #pragma unroll
;         for (int i = 0; i < 8; ++i) ssv[i] = SS[(size_t)(row0 + (i >> 2) * 128 + (i & 3) * 16)];
; #pragma unroll
;         for (int ai = 0; ai < 2; ++ai)
; #pragma unroll
;             for (int m = 0; m < 4; ++m) {
;                 const size_t row = (size_t)(row0 + ai * 128 + m * 16);
;                 const float rs = __builtin_amdgcn_rsqf(ssv[ai * 4 + m] * (1.0f / 1024.0f) + EPS);
;                 const float c1 = -rs * 1.4426950408889634f, rs2 = rs * rs;
;                 f32x4 o[2];
; #pragma unroll
;                 for (int n = 0; n < 2; ++n)
; #pragma unroll
;                     for (int j = 0; j < 4; ++j) { const float ga = acc[ai][0][m][n][j], ua = acc[ai][1][m][n][j];
;                         o[n][j] = (ga * ua) * (rs2 * __builtin_amdgcn_rcpf(1.0f + __builtin_amdgcn_exp2f(ga * c1))); }
;                 __builtin_nontemporal_store(pack8(o[0], o[1]), (u32x4*)(GU + row * DFF + col0));
;             }
.LBB0_1388:
	v_lshl_add_u32 v144, s42, 8, v146
	v_ashrrev_i32_e32 v145, 31, v144
	v_lshl_add_u64 v[154:155], v[144:145], 2, s[14:15]
	global_load_dword v145, v[154:155], off
	global_load_dword v153, v[154:155], off offset:64
	v_mov_b32_e32 v160, v124
	v_mov_b32_e32 v164, v126
	v_mov_b32_e32 v178, v104
	global_load_dword v182, v[154:155], off offset:128
	global_load_dword v183, v[154:155], off offset:192
	global_load_dword v184, v[154:155], off offset:512
	global_load_dword v126, v[154:155], off offset:576
	global_load_dword v124, v[154:155], off offset:640
	global_load_dword v104, v[154:155], off offset:704
	v_lshl_or_b32 v156, s61, 7, v148
	v_ashrrev_i32_e32 v157, 31, v156
	v_mov_b32_e32 v172, v122
	v_mov_b32_e32 v174, v123
	v_lshlrev_b64 v[122:123], 1, v[156:157]
	v_mov_b32_e32 v158, v116
	v_mov_b32_e32 v176, v108
	v_mov_b32_e32 v168, v120
	v_mov_b32_e32 v170, v121
	v_mov_b64_e32 v[120:121], s[8:9]
	v_mad_i64_i32 v[180:181], s[30:31], v144, s60, v[120:121]
	v_lshl_add_u64 v[154:155], v[180:181], 0, v[122:123]
	v_mov_b32_e32 v162, v125
	v_mov_b32_e32 v166, v127
	v_or_b32_e32 v127, 16, v144
	v_add_u32_e32 v125, 0x80, v144
	s_andn2_b64 vcc, exec, s[4:5]
	s_mov_b64 s[4:5], -1
	s_waitcnt vmcnt(0)
	v_fmamk_f32 v226, v145, 0x3a800000, v152
	v_rsq_f32_e32 v145, v226
	v_fmamk_f32 v227, v153, 0x3a800000, v152
	v_rsq_f32_e32 v153, v227
	v_mul_f32_e32 v156, 0xbfb8aa3b, v145
	v_mul_f32_e32 v145, 0xbfb8aa3b, v153
	v_mul_f32_e32 v116, v116, v156
	v_mul_f32_e32 v153, v117, v156
	v_mul_f32_e32 v161, v119, v156
	v_mul_f32_e32 v163, v112, v156
	v_mul_f32_e32 v167, v114, v156
	v_mul_f32_e32 v108, v108, v145
	v_exp_f32_e32 v116, v116
	v_mul_f32_e32 v157, v118, v156
	v_mul_f32_e32 v169, v109, v145
	v_exp_f32_e32 v153, v153
	v_exp_f32_e32 v161, v161
	v_exp_f32_e32 v163, v163
	v_exp_f32_e32 v167, v167
	v_exp_f32_e32 v108, v108
	v_mul_f32_e32 v165, v113, v156
	v_exp_f32_e32 v157, v157
	v_exp_f32_e32 v169, v169
	v_exp_f32_e32 v165, v165
	v_fma_f32 v116, v116, v226, v226
	v_fma_f32 v153, v153, v226, v226
	v_fma_f32 v171, v161, v226, v226
	v_fma_f32 v173, v163, v226, v226
	v_fma_f32 v179, v167, v226, v226
	v_fma_f32 v108, v108, v227, v227
	v_rcp_f32_e32 v161, v116
	v_mul_f32_e32 v156, v115, v156
	v_fma_f32 v157, v157, v226, v226
	v_fma_f32 v180, v169, v227, v227
	v_rcp_f32_e32 v163, v153
	v_rcp_f32_e32 v169, v173
	v_rcp_f32_e32 v173, v179
	v_rcp_f32_e32 v179, v108
	v_exp_f32_e32 v156, v156
	v_fma_f32 v175, v165, v226, v226
	v_rcp_f32_e32 v165, v157
	v_rcp_f32_e32 v167, v171
	v_mul_f32_e32 v160, v158, v160
	v_mov_b32_e32 v158, v117
	v_rcp_f32_e32 v171, v175
	v_mul_f32_e32 v116, v176, v178
	v_mov_b32_e32 v176, v109
	v_mul_f32_e32 v108, v158, v162
	v_fma_f32 v156, v156, v226, v226
	v_mul_f32_e32 v116, v116, v179
	v_mul_f32_e32 v117, v108, v163
	v_mul_f32_e32 v108, v118, v164
	v_rcp_f32_e32 v175, v156
	v_mul_f32_e32 v118, v108, v165
	v_mul_f32_e32 v108, v119, v166
	v_mov_b32_e32 v158, v112
	v_mul_f32_e32 v153, v160, v161
	v_cvt_pk_bf16_f32 v112, v153, v117
	v_mul_f32_e32 v117, v108, v167
	v_mul_f32_e32 v108, v158, v168
	v_mul_f32_e32 v119, v108, v169
	v_mul_f32_e32 v108, v113, v170
	v_mov_b32_e32 v158, v114
	v_mul_f32_e32 v114, v108, v171
	v_mul_f32_e32 v108, v158, v172
	v_mov_b32_e32 v158, v115
	v_mul_f32_e32 v115, v108, v173
	v_mul_f32_e32 v108, v158, v174
	v_rcp_f32_e32 v157, v180
	v_mul_f32_e32 v108, v108, v175
	v_cvt_pk_bf16_f32 v115, v115, v108
	v_mul_f32_e32 v108, v110, v145
	v_cvt_pk_bf16_f32 v113, v118, v117
	v_cvt_pk_bf16_f32 v114, v119, v114
	global_store_dwordx4 v[154:155], v[112:115], off nt
	v_mov_b32_e32 v156, v105
	s_nop 0
	v_exp_f32_e32 v112, v108
	v_mul_f32_e32 v108, v176, v105
	v_mov_b32_e32 v176, v110
	v_mul_f32_e32 v105, v108, v157
	v_fma_f32 v108, v112, v227, v227
	v_rcp_f32_e32 v109, v108
	v_mul_f32_e32 v108, v111, v145
	v_exp_f32_e32 v110, v108
	v_mul_f32_e32 v108, v176, v106
	v_fma_f32 v106, v110, v227, v227
	v_mul_f32_e32 v112, v108, v109
	v_rcp_f32_e32 v109, v106
	v_mul_f32_e32 v106, v100, v145
	v_exp_f32_e32 v110, v106
	v_mul_f32_e32 v106, v111, v107
	v_mov_b32_e32 v176, v100
	v_mul_f32_e32 v108, v106, v109
	v_fma_f32 v106, v110, v227, v227
	v_mul_f32_e32 v100, v101, v145
	v_rcp_f32_e32 v107, v106
	v_exp_f32_e32 v100, v100
	v_mul_f32_e32 v106, v176, v96
	v_fma_f32 v96, v100, v227, v227
	v_mul_f32_e32 v109, v106, v107
	v_rcp_f32_e32 v107, v96
	v_mul_f32_e32 v96, v102, v145
	v_exp_f32_e32 v100, v96
	v_mul_f32_e32 v96, v101, v97
	v_mul_f32_e32 v106, v96, v107
	v_fma_f32 v96, v100, v227, v227
	v_rcp_f32_e32 v97, v96
	v_mul_f32_e32 v96, v103, v145
	v_exp_f32_e32 v100, v96
	v_mul_f32_e32 v96, v102, v98
	v_mov_b32_e32 v176, v103
	v_fma_f32 v98, v100, v227, v227
	v_rcp_f32_e32 v101, v98
	v_mul_f32_e32 v102, v96, v97
	v_cvt_pk_bf16_f32 v98, v109, v106
	v_mul_f32_e32 v96, v103, v99
	v_fmamk_f32 v228, v182, 0x3a800000, v152
	v_mul_f32_e32 v99, v96, v101
	v_cvt_pk_bf16_f32 v99, v102, v99
	v_rsq_f32_e32 v102, v228
	v_cvt_pk_bf16_f32 v96, v116, v105
	v_mad_i64_i32 v[100:101], s[30:31], v127, s60, v[120:121]
	v_mul_f32_e32 v103, 0xbfb8aa3b, v102
	v_mul_f32_e32 v105, v92, v103
	v_exp_f32_e32 v105, v105
	v_lshl_add_u64 v[100:101], v[100:101], 0, v[122:123]
	v_cvt_pk_bf16_f32 v97, v112, v108
	global_store_dwordx4 v[100:101], v[96:99], off nt
	v_or_b32_e32 v100, 32, v144
	s_nop 0
	v_fma_f32 v96, v105, v228, v228
	v_rcp_f32_e32 v99, v96
	v_mov_b32_e32 v96, v92
	v_mul_f32_e32 v92, v93, v103
	v_exp_f32_e32 v92, v92
	v_mul_f32_e32 v98, v96, v88
	v_fma_f32 v88, v92, v228, v228
	v_mul_f32_e32 v101, v98, v99
	v_rcp_f32_e32 v99, v88
	v_mul_f32_e32 v88, v94, v103
	v_exp_f32_e32 v92, v88
	v_mov_b32_e32 v98, v89
	v_mul_f32_e32 v88, v93, v89
	v_mul_f32_e32 v93, v88, v99
; DI u32x4 pack8(const f32x4 v0, const f32x4 v1) { u32x4 w; w.x = cvt_pk_bf16(v0[0], v0[1]); w.y = cvt_pk_bf16(v0[2], v0[3]); w.z = cvt_pk_bf16(v1[0], v1[1]); w.w = cvt_pk_bf16(v1[2], v1[3]); return w; }
;     DI void operator()(const f32x4 (&acc)[2][2][4][2], const Unit& u, int wr, int wc, int fr, int fq) const {
;     ...
; #pragma unroll
;         for (int ai = 0; ai < 2; ++ai)
; #pragma unroll
;             for (int m = 0; m < 4; ++m) {
;                 const size_t row = (size_t)(row0 + ai * 128 + m * 16);
;                 const float rs = __builtin_amdgcn_rsqf(ssv[ai * 4 + m] * (1.0f / 1024.0f) + EPS);
;                 const float c1 = -rs * 1.4426950408889634f, rs2 = rs * rs;
;                 f32x4 o[2];
; #pragma unroll
;                 for (int n = 0; n < 2; ++n)
; #pragma unroll
;                     for (int j = 0; j < 4; ++j) { const float ga = acc[ai][0][m][n][j], ua = acc[ai][1][m][n][j];
;                         o[n][j] = (ga * ua) * (rs2 * __builtin_amdgcn_rcpf(1.0f + __builtin_amdgcn_exp2f(ga * c1))); }
;                 __builtin_nontemporal_store(pack8(o[0], o[1]), (u32x4*)(GU + row * DFF + col0));
;             }
	v_fma_f32 v88, v92, v228, v228
	v_rcp_f32_e32 v89, v88
	v_mul_f32_e32 v88, v95, v103
	v_exp_f32_e32 v92, v88
	v_mul_f32_e32 v88, v94, v90
	v_mul_f32_e32 v90, v88, v89
	v_fma_f32 v88, v92, v228, v228
	v_rcp_f32_e32 v89, v88
	v_mul_f32_e32 v88, v84, v103
	v_exp_f32_e32 v92, v88
	v_mul_f32_e32 v88, v95, v91
	v_mov_b32_e32 v96, v84
	v_mul_f32_e32 v91, v88, v89
	v_fma_f32 v88, v92, v228, v228
	v_mul_f32_e32 v84, v85, v103
	v_rcp_f32_e32 v89, v88
	v_exp_f32_e32 v84, v84
	v_mul_f32_e32 v88, v96, v80
	v_fma_f32 v80, v84, v228, v228
	v_mul_f32_e32 v92, v88, v89
	v_rcp_f32_e32 v89, v80
	v_mul_f32_e32 v80, v86, v103
	v_exp_f32_e32 v84, v80
	v_mul_f32_e32 v80, v85, v81
	v_mul_f32_e32 v88, v80, v89
	v_fma_f32 v80, v84, v228, v228
	v_rcp_f32_e32 v81, v80
	v_mul_f32_e32 v80, v87, v103
	v_exp_f32_e32 v84, v80
	v_mul_f32_e32 v80, v86, v82
	v_mov_b32_e32 v96, v87
	v_fma_f32 v82, v84, v228, v228
	v_rcp_f32_e32 v85, v82
	v_mul_f32_e32 v86, v80, v81
	v_cvt_pk_bf16_f32 v82, v92, v88
	v_mul_f32_e32 v80, v87, v83
	v_fmamk_f32 v229, v183, 0x3a800000, v152
	v_mul_f32_e32 v83, v80, v85
	v_cvt_pk_bf16_f32 v83, v86, v83
	v_rsq_f32_e32 v86, v229
	v_mad_i64_i32 v[84:85], s[30:31], v100, s60, v[120:121]
	v_cvt_pk_bf16_f32 v80, v101, v93
	v_mul_f32_e32 v87, 0xbfb8aa3b, v86
	v_mul_f32_e32 v88, v76, v87
	v_exp_f32_e32 v88, v88
	v_lshl_add_u64 v[84:85], v[84:85], 0, v[122:123]
	v_cvt_pk_bf16_f32 v81, v90, v91
	global_store_dwordx4 v[84:85], v[80:83], off nt
	v_or_b32_e32 v84, 48, v144
	s_nop 0
	v_fma_f32 v80, v88, v229, v229
	v_rcp_f32_e32 v83, v80
	v_mov_b32_e32 v80, v76
	v_mul_f32_e32 v76, v77, v87
	v_exp_f32_e32 v76, v76
	v_mul_f32_e32 v82, v80, v72
	v_fma_f32 v72, v76, v229, v229
	v_mul_f32_e32 v85, v82, v83
	v_rcp_f32_e32 v83, v72
	v_mul_f32_e32 v72, v78, v87
	v_exp_f32_e32 v76, v72
	v_mov_b32_e32 v82, v73
	v_mul_f32_e32 v72, v77, v73
	v_mul_f32_e32 v77, v72, v83
	v_fma_f32 v72, v76, v229, v229
	v_rcp_f32_e32 v73, v72
	v_mul_f32_e32 v72, v79, v87
	v_exp_f32_e32 v76, v72
	v_mul_f32_e32 v72, v78, v74
	v_mul_f32_e32 v74, v72, v73
	v_fma_f32 v72, v76, v229, v229
	v_rcp_f32_e32 v73, v72
	v_mul_f32_e32 v72, v68, v87
	v_exp_f32_e32 v76, v72
	v_mul_f32_e32 v72, v79, v75
	v_mov_b32_e32 v80, v68
	v_mul_f32_e32 v75, v72, v73
	v_fma_f32 v72, v76, v229, v229
	v_mul_f32_e32 v68, v69, v87
	v_rcp_f32_e32 v73, v72
	v_exp_f32_e32 v68, v68
	v_mul_f32_e32 v72, v80, v64
	v_fma_f32 v64, v68, v229, v229
	v_mul_f32_e32 v76, v72, v73
	v_rcp_f32_e32 v73, v64
	v_mul_f32_e32 v64, v70, v87
	v_exp_f32_e32 v68, v64
	v_mul_f32_e32 v64, v69, v65
	v_mul_f32_e32 v72, v64, v73
	v_fma_f32 v64, v68, v229, v229
	v_rcp_f32_e32 v65, v64
	v_mul_f32_e32 v64, v71, v87
	v_exp_f32_e32 v68, v64
	v_mul_f32_e32 v64, v70, v66
	v_mov_b32_e32 v80, v71
	v_fma_f32 v66, v68, v229, v229
	v_rcp_f32_e32 v69, v66
	v_mul_f32_e32 v70, v64, v65
	v_cvt_pk_bf16_f32 v66, v76, v72
	v_mul_f32_e32 v64, v71, v67
	v_fmamk_f32 v230, v184, 0x3a800000, v152
	v_rsq_f32_e32 v71, v230
	v_mul_f32_e32 v67, v64, v69
	v_cvt_pk_bf16_f32 v67, v70, v67
	v_mad_i64_i32 v[68:69], s[30:31], v84, s60, v[120:121]
	v_mul_f32_e32 v70, 0xbfb8aa3b, v71
	v_mul_f32_e32 v72, v60, v70
	v_exp_f32_e32 v72, v72
	v_cvt_pk_bf16_f32 v64, v85, v77
	v_lshl_add_u64 v[68:69], v[68:69], 0, v[122:123]
	v_cvt_pk_bf16_f32 v65, v74, v75
	global_store_dwordx4 v[68:69], v[64:67], off nt
	s_nop 1
	v_fma_f32 v64, v72, v230, v230
	v_rcp_f32_e32 v67, v64
	v_mov_b32_e32 v64, v60
	v_mul_f32_e32 v60, v61, v70
	v_exp_f32_e32 v60, v60
	v_mul_f32_e32 v66, v64, v56
	v_fma_f32 v56, v60, v230, v230
	v_mul_f32_e32 v68, v66, v67
	v_rcp_f32_e32 v67, v56
	v_mul_f32_e32 v56, v62, v70
	v_exp_f32_e32 v60, v56
	v_mov_b32_e32 v66, v57
	v_mul_f32_e32 v56, v61, v57
	v_mul_f32_e32 v61, v56, v67
	v_fma_f32 v56, v60, v230, v230
	v_rcp_f32_e32 v57, v56
	v_mul_f32_e32 v56, v63, v70
	v_exp_f32_e32 v60, v56
	v_mul_f32_e32 v56, v62, v58
	v_mul_f32_e32 v58, v56, v57
	v_fma_f32 v56, v60, v230, v230
	v_rcp_f32_e32 v57, v56
	v_mul_f32_e32 v56, v52, v70
	v_exp_f32_e32 v60, v56
	v_mul_f32_e32 v56, v63, v59
	v_mov_b32_e32 v64, v52
	v_mul_f32_e32 v59, v56, v57
	v_fma_f32 v56, v60, v230, v230
	v_mul_f32_e32 v52, v53, v70
	v_rcp_f32_e32 v57, v56
	v_exp_f32_e32 v52, v52
	v_mul_f32_e32 v56, v64, v48
	v_fma_f32 v48, v52, v230, v230
	v_mul_f32_e32 v60, v56, v57
	v_rcp_f32_e32 v57, v48
	v_mul_f32_e32 v48, v54, v70
	v_exp_f32_e32 v52, v48
	v_mul_f32_e32 v48, v53, v49
	v_mul_f32_e32 v56, v48, v57
	v_fma_f32 v48, v52, v230, v230
	v_rcp_f32_e32 v49, v48
	v_mul_f32_e32 v48, v55, v70
	v_exp_f32_e32 v52, v48
	v_mul_f32_e32 v48, v54, v50
	v_mov_b32_e32 v64, v55
	v_fma_f32 v50, v52, v230, v230
	v_rcp_f32_e32 v53, v50
	v_mul_f32_e32 v54, v48, v49
	v_cvt_pk_bf16_f32 v50, v60, v56
	v_mul_f32_e32 v48, v55, v51
	v_fmamk_f32 v231, v126, 0x3a800000, v152
	v_mul_f32_e32 v51, v48, v53
	v_cvt_pk_bf16_f32 v51, v54, v51
	v_rsq_f32_e32 v54, v231
	v_mad_i64_i32 v[52:53], s[30:31], v125, s60, v[120:121]
	v_cvt_pk_bf16_f32 v48, v68, v61
	v_mul_f32_e32 v55, 0xbfb8aa3b, v54
	v_mul_f32_e32 v56, v44, v55
	v_exp_f32_e32 v56, v56
	v_lshl_add_u64 v[52:53], v[52:53], 0, v[122:123]
	v_cvt_pk_bf16_f32 v49, v58, v59
	global_store_dwordx4 v[52:53], v[48:51], off nt
	v_add_u32_e32 v52, 0x90, v144
	s_nop 0
	v_fma_f32 v48, v56, v231, v231
	v_rcp_f32_e32 v51, v48
	v_mov_b32_e32 v48, v44
	v_mul_f32_e32 v44, v45, v55
	v_exp_f32_e32 v44, v44
; DI u32x4 pack8(const f32x4 v0, const f32x4 v1) { u32x4 w; w.x = cvt_pk_bf16(v0[0], v0[1]); w.y = cvt_pk_bf16(v0[2], v0[3]); w.z = cvt_pk_bf16(v1[0], v1[1]); w.w = cvt_pk_bf16(v1[2], v1[3]); return w; }
;     DI void operator()(const f32x4 (&acc)[2][2][4][2], const Unit& u, int wr, int wc, int fr, int fq) const {
;     ...
;             for (int m = 0; m < 4; ++m) {
;                 const size_t row = (size_t)(row0 + ai * 128 + m * 16);
;                 const float rs = __builtin_amdgcn_rsqf(ssv[ai * 4 + m] * (1.0f / 1024.0f) + EPS);
;                 const float c1 = -rs * 1.4426950408889634f, rs2 = rs * rs;
;                 f32x4 o[2];
; #pragma unroll
;                 for (int n = 0; n < 2; ++n)
; #pragma unroll
;                     for (int j = 0; j < 4; ++j) { const float ga = acc[ai][0][m][n][j], ua = acc[ai][1][m][n][j];
;                         o[n][j] = (ga * ua) * (rs2 * __builtin_amdgcn_rcpf(1.0f + __builtin_amdgcn_exp2f(ga * c1))); }
;                 __builtin_nontemporal_store(pack8(o[0], o[1]), (u32x4*)(GU + row * DFF + col0));
	v_mul_f32_e32 v50, v48, v40
	v_fma_f32 v40, v44, v231, v231
	v_mul_f32_e32 v53, v50, v51
	v_rcp_f32_e32 v51, v40
	v_mul_f32_e32 v40, v46, v55
	v_exp_f32_e32 v44, v40
	v_mov_b32_e32 v50, v41
	v_mul_f32_e32 v40, v45, v41
	v_mul_f32_e32 v45, v40, v51
	v_fma_f32 v40, v44, v231, v231
	v_rcp_f32_e32 v41, v40
	v_mul_f32_e32 v40, v47, v55
	v_exp_f32_e32 v44, v40
	v_mul_f32_e32 v40, v46, v42
	v_mul_f32_e32 v42, v40, v41
	v_fma_f32 v40, v44, v231, v231
	v_rcp_f32_e32 v41, v40
	v_mul_f32_e32 v40, v36, v55
	v_exp_f32_e32 v44, v40
	v_mul_f32_e32 v40, v47, v43
	v_mov_b32_e32 v48, v36
	v_mul_f32_e32 v43, v40, v41
	v_fma_f32 v40, v44, v231, v231
	v_mul_f32_e32 v36, v37, v55
	v_rcp_f32_e32 v41, v40
	v_exp_f32_e32 v36, v36
	v_mul_f32_e32 v40, v48, v32
	v_fma_f32 v32, v36, v231, v231
	v_mul_f32_e32 v44, v40, v41
	v_rcp_f32_e32 v41, v32
	v_mul_f32_e32 v32, v38, v55
	v_exp_f32_e32 v36, v32
	v_mul_f32_e32 v32, v37, v33
	v_mul_f32_e32 v40, v32, v41
	v_fma_f32 v32, v36, v231, v231
	v_rcp_f32_e32 v33, v32
	v_mul_f32_e32 v32, v39, v55
	v_exp_f32_e32 v36, v32
	v_mul_f32_e32 v32, v38, v34
	v_mov_b32_e32 v48, v39
	v_fma_f32 v34, v36, v231, v231
	v_rcp_f32_e32 v37, v34
	v_mul_f32_e32 v38, v32, v33
	v_cvt_pk_bf16_f32 v34, v44, v40
	v_mul_f32_e32 v32, v39, v35
	v_fmamk_f32 v232, v124, 0x3a800000, v152
	v_mul_f32_e32 v35, v32, v37
	v_cvt_pk_bf16_f32 v35, v38, v35
	v_rsq_f32_e32 v38, v232
	v_mad_i64_i32 v[36:37], s[30:31], v52, s60, v[120:121]
	v_cvt_pk_bf16_f32 v32, v53, v45
	v_mul_f32_e32 v39, 0xbfb8aa3b, v38
	v_mul_f32_e32 v40, v28, v39
	v_exp_f32_e32 v40, v40
	v_lshl_add_u64 v[36:37], v[36:37], 0, v[122:123]
	v_cvt_pk_bf16_f32 v33, v42, v43
	global_store_dwordx4 v[36:37], v[32:35], off nt
	v_add_u32_e32 v36, 0xa0, v144
	s_nop 0
	v_fma_f32 v32, v40, v232, v232
	v_rcp_f32_e32 v35, v32
	v_mov_b32_e32 v32, v28
	v_mul_f32_e32 v28, v29, v39
	v_exp_f32_e32 v28, v28
	v_mul_f32_e32 v34, v32, v24
	v_fma_f32 v24, v28, v232, v232
	v_mul_f32_e32 v37, v34, v35
	v_rcp_f32_e32 v35, v24
	v_mul_f32_e32 v24, v30, v39
	v_exp_f32_e32 v28, v24
	v_mov_b32_e32 v34, v25
	v_mul_f32_e32 v24, v29, v25
	v_mul_f32_e32 v29, v24, v35
	v_fma_f32 v24, v28, v232, v232
	v_rcp_f32_e32 v25, v24
	v_mul_f32_e32 v24, v31, v39
	v_exp_f32_e32 v28, v24
	v_mul_f32_e32 v24, v30, v26
	v_mul_f32_e32 v26, v24, v25
	v_fma_f32 v24, v28, v232, v232
	v_rcp_f32_e32 v25, v24
	v_mul_f32_e32 v24, v20, v39
	v_exp_f32_e32 v28, v24
	v_mul_f32_e32 v24, v31, v27
	v_mov_b32_e32 v32, v20
	v_mul_f32_e32 v27, v24, v25
	v_fma_f32 v24, v28, v232, v232
	v_mul_f32_e32 v20, v21, v39
	v_rcp_f32_e32 v25, v24
	v_exp_f32_e32 v20, v20
	v_mul_f32_e32 v24, v32, v16
	v_fma_f32 v16, v20, v232, v232
	v_mul_f32_e32 v28, v24, v25
	v_rcp_f32_e32 v25, v16
	v_mul_f32_e32 v16, v22, v39
	v_exp_f32_e32 v20, v16
	v_mul_f32_e32 v16, v21, v17
	v_mul_f32_e32 v24, v16, v25
	v_fma_f32 v16, v20, v232, v232
	v_rcp_f32_e32 v17, v16
	v_mul_f32_e32 v16, v23, v39
	v_exp_f32_e32 v20, v16
	v_mul_f32_e32 v16, v22, v18
	v_mov_b32_e32 v32, v23
	v_fma_f32 v18, v20, v232, v232
	v_rcp_f32_e32 v21, v18
	v_mul_f32_e32 v22, v16, v17
	v_cvt_pk_bf16_f32 v18, v28, v24
	v_mul_f32_e32 v16, v23, v19
	v_fmamk_f32 v233, v104, 0x3a800000, v152
	v_mul_f32_e32 v19, v16, v21
	v_cvt_pk_bf16_f32 v19, v22, v19
	v_rsq_f32_e32 v22, v233
	v_mad_i64_i32 v[20:21], s[30:31], v36, s60, v[120:121]
	v_cvt_pk_bf16_f32 v16, v37, v29
	v_mul_f32_e32 v23, 0xbfb8aa3b, v22
	v_mul_f32_e32 v24, v12, v23
	v_exp_f32_e32 v24, v24
	v_lshl_add_u64 v[20:21], v[20:21], 0, v[122:123]
	v_cvt_pk_bf16_f32 v17, v26, v27
	global_store_dwordx4 v[20:21], v[16:19], off nt
	v_add_u32_e32 v20, 0xb0, v144
	s_nop 0
	v_fma_f32 v16, v24, v233, v233
	v_rcp_f32_e32 v19, v16
	v_mov_b32_e32 v16, v12
	v_mul_f32_e32 v12, v13, v23
	v_exp_f32_e32 v12, v12
	v_mul_f32_e32 v17, v22, v22
	v_mul_f32_e32 v18, v16, v8
	v_fma_f32 v8, v12, v233, v233
	v_mul_f32_e32 v21, v18, v19
	v_rcp_f32_e32 v19, v8
	v_mul_f32_e32 v8, v14, v23
	v_exp_f32_e32 v12, v8
	v_mov_b32_e32 v18, v9
	v_mul_f32_e32 v8, v13, v9
	v_mul_f32_e32 v13, v8, v19
	v_fma_f32 v8, v12, v233, v233
	v_rcp_f32_e32 v9, v8
	v_mul_f32_e32 v8, v15, v23
	v_exp_f32_e32 v12, v8
	v_mul_f32_e32 v8, v14, v10
	v_mul_f32_e32 v10, v8, v9
	v_fma_f32 v8, v12, v233, v233
	v_rcp_f32_e32 v9, v8
	v_mul_f32_e32 v8, v4, v23
	v_exp_f32_e32 v12, v8
	v_mul_f32_e32 v8, v15, v11
	v_mov_b32_e32 v16, v4
	v_mul_f32_e32 v11, v8, v9
	v_fma_f32 v8, v12, v233, v233
	v_mul_f32_e32 v4, v5, v23
	v_rcp_f32_e32 v9, v8
	v_exp_f32_e32 v4, v4
	v_mul_f32_e32 v8, v16, v0
	v_fma_f32 v0, v4, v233, v233
	v_mul_f32_e32 v12, v8, v9
	v_rcp_f32_e32 v9, v0
	v_mul_f32_e32 v0, v6, v23
	v_exp_f32_e32 v4, v0
	v_mul_f32_e32 v0, v5, v1
	v_mul_f32_e32 v8, v0, v9
	v_fma_f32 v0, v4, v233, v233
	v_rcp_f32_e32 v1, v0
	v_mul_f32_e32 v0, v7, v23
	v_exp_f32_e32 v4, v0
	v_mul_f32_e32 v0, v6, v2
	v_mov_b32_e32 v16, v7
	v_add_f32_e32 v2, 1.0, v4
	v_rcp_f32_e32 v5, v2
	v_mul_f32_e32 v6, v0, v1
	v_cvt_pk_bf16_f32 v2, v12, v8
	v_mul_f32_e32 v0, v7, v3
	v_mul_f32_e32 v1, v17, v5
	v_mad_i64_i32 v[4:5], s[30:31], v20, s60, v[120:121]
	v_mul_f32_e32 v3, v0, v1
	v_lshl_add_u64 v[4:5], v[4:5], 0, v[122:123]
	v_cvt_pk_bf16_f32 v0, v21, v13
	v_cvt_pk_bf16_f32 v1, v10, v11
	v_cvt_pk_bf16_f32 v3, v6, v3
	global_store_dwordx4 v[4:5], v[0:3], off nt
	s_cbranch_vccnz .LBB0_1381
	s_andn2_b64 vcc, exec, s[6:7]
	s_cbranch_vccnz .LBB0_1380
	s_barrier
	s_branch .LBB0_1380
